# one early buffer_wbl2 per XCD when 75 percent of its workgroups have arrived, on top of TOP polling and early invalidate
# speedup vs baseline: 1.0187x; 1.0040x over previous
; __device__ __forceinline__ unsigned xb_ld(unsigned* p)              { return __hip_atomic_load(p, __ATOMIC_RELAXED, __HIP_MEMORY_SCOPE_AGENT); }
; __device__ __forceinline__ unsigned xb_add(unsigned* p, unsigned v) { return __hip_atomic_fetch_add(p, v, __ATOMIC_RELAXED, __HIP_MEMORY_SCOPE_AGENT); }
; #define XB_SPIN(cond, bar) do { unsigned _sp = 0; while (cond) { __builtin_amdgcn_s_sleep(0); \
;     if ((++_sp & 255u) == 0u) { if (xb_ld(&(bar)[XB_TMO])) break; if (_sp > XB_SPIN_CAP) { atomicAdd(&(bar)[XB_TMO], 1u); break; } } } } while (0)
; __device__ __forceinline__ void xcd_barrier(const XcdBarrier& b) {
;     ...
;         const unsigned old = xb_add(&bar[XB_XSUB(b.x)], 1u);
;         const unsigned gen = old / nloc;
;         if (old + 1u == (gen + 1u) * nloc) {
;             __builtin_amdgcn_fence(__ATOMIC_RELEASE, "agent");
;     ...
;             XB_SPIN(xb_ld(&bar[XB_XGEN(b.x)]) == gen, bar);
.LBB0_155:
	s_or_b64 exec, exec, s[0:1]
	v_cvt_f32_u32_e32 v4, v2
	s_waitcnt vmcnt(0)
	v_readfirstlane_b32 s0, v3
	v_sub_u32_e32 v3, 0, v2
	v_rcp_iflag_f32_e32 v4, v4
	v_add_u32_e32 v5, s0, v1
	v_mul_f32_e32 v4, 0x4f7ffffe, v4
	v_cvt_u32_f32_e32 v4, v4
	v_mul_lo_u32 v1, v3, v4
	v_mul_hi_u32 v1, v4, v1
	v_add_u32_e32 v1, v4, v1
	v_mul_hi_u32 v1, v5, v1
	v_mul_lo_u32 v3, v1, v2
	v_sub_u32_e32 v3, v5, v3
	v_add_u32_e32 v4, 1, v1
	v_cmp_ge_u32_e32 vcc, v3, v2
	s_nop 1
	v_cndmask_b32_e32 v1, v1, v4, vcc
	v_sub_u32_e32 v4, v3, v2
	v_cndmask_b32_e32 v3, v3, v4, vcc
	v_add_u32_e32 v4, 1, v1
	v_cmp_ge_u32_e32 vcc, v3, v2
	v_add_u32_e32 v3, 1, v5
	s_nop 0
	v_cndmask_b32_e32 v1, v1, v4, vcc
	v_mul_lo_u32 v4, v2, v1
	v_add_u32_e32 v2, v4, v2
	v_cmp_ne_u32_e32 vcc, v3, v2
	s_and_saveexec_b64 s[0:1], vcc
	s_xor_b64 s[0:1], exec, s[0:1]
	s_cbranch_execz .LBB0_169
	v_readlane_b32 s2, v252, 7
	v_readlane_b32 s3, v252, 8
	s_waitcnt lgkmcnt(0)
	v_mad_u32_u24 v1, v0, v1, v0
	v_sub_u32_e32 v3, v3, v4
	v_sub_u32_e32 v4, v2, v4
	v_lshlrev_b32_e32 v3, 2, v3
	v_mul_u32_u24_e32 v4, 3, v4
	v_cmp_eq_u32_e32 vcc, v3, v4
	s_cbranch_vccz .Lewb_skip0
	buffer_wbl2 sc1
.Lewb_skip0:
	s_nop 3
	global_load_dword v0, v17, s[2:3] sc1
	s_waitcnt vmcnt(0)
	v_cmp_lt_u32_e32 vcc, v0, v1
	s_and_saveexec_b64 s[2:3], vcc
	s_cbranch_execz .LBB0_168
	s_mov_b32 s17, 1
	s_mov_b64 s[6:7], 0
	s_branch .LBB0_159

; __device__ __forceinline__ unsigned xb_ld(unsigned* p)              { return __hip_atomic_load(p, __ATOMIC_RELAXED, __HIP_MEMORY_SCOPE_AGENT); }
; #define XB_SPIN(cond, bar) do { unsigned _sp = 0; while (cond) { __builtin_amdgcn_s_sleep(0); \
;     if ((++_sp & 255u) == 0u) { if (xb_ld(&(bar)[XB_TMO])) break; if (_sp > XB_SPIN_CAP) { atomicAdd(&(bar)[XB_TMO], 1u); break; } } } } while (0)
; __device__ __forceinline__ void xcd_barrier(const XcdBarrier& b) {
;     ...
;         } else {
;             XB_SPIN(xb_ld(&bar[XB_XGEN(b.x)]) == gen, bar);
.Lewb_skip1:
	s_nop 3
	global_load_dword v0, v17, s[2:3] sc1
	s_waitcnt vmcnt(0)
	v_cmp_lt_u32_e32 vcc, v0, v1
	s_and_saveexec_b64 s[2:3], vcc
	s_cbranch_execz .LBB0_257
	s_mov_b32 s19, 1
	s_mov_b64 s[8:9], 0
	s_branch .LBB0_248

; __device__ __forceinline__ unsigned xb_ld(unsigned* p)              { return __hip_atomic_load(p, __ATOMIC_RELAXED, __HIP_MEMORY_SCOPE_AGENT); }
; #define XB_SPIN(cond, bar) do { unsigned _sp = 0; while (cond) { __builtin_amdgcn_s_sleep(0); \
;     if ((++_sp & 255u) == 0u) { if (xb_ld(&(bar)[XB_TMO])) break; if (_sp > XB_SPIN_CAP) { atomicAdd(&(bar)[XB_TMO], 1u); break; } } } } while (0)
; __device__ __forceinline__ void xcd_barrier(const XcdBarrier& b) {
;     ...
;         } else {
;             XB_SPIN(xb_ld(&bar[XB_XGEN(b.x)]) == gen, bar);
.Lewb_skip10:
	s_nop 3
	global_load_dword v0, v17, s[2:3] sc1
	s_waitcnt vmcnt(0)
	v_cmp_lt_u32_e32 vcc, v0, v1
	s_and_saveexec_b64 s[2:3], vcc
	s_cbranch_execz .LBB0_2010
	s_mov_b32 s16, 1
	s_mov_b64 s[6:7], 0
	s_branch .LBB0_2001
